# down-GEMM layer-0 epilogue (bf16 residual in place, A' and row sum-squares) hand-written straight-line with the same 5-deep load pipeline
# baseline (speedup 1.0000x reference)
.LBB0_1058:
	s_lshl_b32 s2, s54, 8
	s_add_i32 s2, s2, s45
	v_add_u32_e32 v184, s2, v186
	v_ashrrev_i32_e32 v185, 31, v184
	v_lshlrev_b64 v[186:187], 10, v[184:185]
	v_lshl_add_u64 v[190:191], v[186:187], 0, v[182:183]
	v_lshl_add_u64 v[186:187], v[190:191], 1, s[16:17]
	s_and_b64 vcc, exec, s[74:75]
	s_cbranch_vccz .Ldown_bc
	v_mov_b32_e32 v222, v186
	v_mov_b32_e32 v223, v187
	global_load_dwordx4 v[206:209], v[222:223], off
	global_load_dwordx4 v[210:213], v[222:223], off offset:256
	s_mov_b64 s[80:81], 0x8000
	v_lshl_add_u64 v[222:223], v[222:223], 0, s[80:81]
	global_load_dwordx4 v[214:217], v[222:223], off
	global_load_dwordx4 v[218:221], v[222:223], off offset:256
	s_mov_b64 s[80:81], 0x8000
	v_lshl_add_u64 v[222:223], v[222:223], 0, s[80:81]
	global_load_dwordx4 v[236:239], v[222:223], off
	s_mov_b64 s[2:3], -1
	s_and_b64 vcc, exec, s[74:75]
	s_waitcnt vmcnt(4)
	v_lshlrev_b32_e32 v188, 16, v206
	v_and_b32_e32 v189, 0xffff0000, v206
	v_lshlrev_b32_e32 v198, 16, v207
	v_and_b32_e32 v199, 0xffff0000, v207
	v_lshlrev_b32_e32 v202, 16, v208
	v_and_b32_e32 v203, 0xffff0000, v208
	v_lshlrev_b32_e32 v200, 16, v209
	v_and_b32_e32 v201, 0xffff0000, v209
	global_load_dwordx4 v[206:209], v[222:223], off offset:256
	v_pk_fma_f32 v[158:159], v[158:159], v[74:75], v[198:199]
	v_pk_fma_f32 v[156:157], v[156:157], v[72:73], v[188:189]
	v_pk_fma_f32 v[154:155], v[154:155], v[86:87], v[200:201]
	v_pk_fma_f32 v[152:153], v[152:153], v[84:85], v[202:203]
	v_lshl_add_u64 v[188:189], v[190:191], 2, s[12:13]
	s_cbranch_vccnz .LBB0_1065
	s_andn2_b64 vcc, exec, s[2:3]
	s_cbranch_vccz .LBB0_1066

.Ldown_bc:
	v_mov_b32_e32 v222, v186
	v_mov_b32_e32 v223, v187
	global_load_dwordx4 v[206:209], v[222:223], off
	global_load_dwordx4 v[210:213], v[222:223], off offset:256
	s_mov_b64 s[80:81], 0x8000
	v_lshl_add_u64 v[222:223], v[222:223], 0, s[80:81]
	global_load_dwordx4 v[214:217], v[222:223], off
	global_load_dwordx4 v[218:221], v[222:223], off offset:256
	s_mov_b64 s[80:81], 0x8000
	v_lshl_add_u64 v[222:223], v[222:223], 0, s[80:81]
	global_load_dwordx4 v[236:239], v[222:223], off
	v_lshl_add_u64 v[190:191], v[190:191], 1, s[18:19]
	v_lshl_add_u64 v[184:185], v[184:185], 2, s[20:21]
	v_cmp_eq_u32_e64 s[8:9], 0, v196
	s_waitcnt vmcnt(4)
	v_lshlrev_b32_e32 v198, 16, v206
	v_and_b32_e32 v199, 0xffff0000, v206
	v_lshlrev_b32_e32 v200, 16, v207
	v_and_b32_e32 v201, 0xffff0000, v207
	v_lshlrev_b32_e32 v202, 16, v208
	v_and_b32_e32 v203, 0xffff0000, v208
	v_lshlrev_b32_e32 v204, 16, v209
	v_and_b32_e32 v205, 0xffff0000, v209
	v_pk_fma_f32 v[156:157], v[156:157], v[72:73], v[198:199]
	v_pk_fma_f32 v[158:159], v[158:159], v[74:75], v[200:201]
	v_pk_fma_f32 v[152:153], v[152:153], v[84:85], v[202:203]
	v_pk_fma_f32 v[154:155], v[154:155], v[86:87], v[204:205]
	v_cvt_pk_bf16_f32 v206, v156, v157
	v_cvt_pk_bf16_f32 v207, v158, v159
	v_cvt_pk_bf16_f32 v208, v152, v153
	v_cvt_pk_bf16_f32 v209, v154, v155
	global_store_dwordx4 v[186:187], v[206:209], off
	v_pk_mul_f32 v[198:199], v[60:61], v[156:157]
	v_pk_mul_f32 v[200:201], v[62:63], v[158:159]
	v_pk_mul_f32 v[202:203], v[52:53], v[152:153]
	v_pk_mul_f32 v[204:205], v[54:55], v[154:155]
	v_pk_mul_f32 v[188:189], v[156:157], v[156:157]
	v_pk_fma_f32 v[188:189], v[158:159], v[158:159], v[188:189]
	v_pk_fma_f32 v[188:189], v[152:153], v[152:153], v[188:189]
	v_pk_fma_f32 v[188:189], v[154:155], v[154:155], v[188:189]
	global_load_dwordx4 v[206:209], v[222:223], off offset:256
	v_cvt_pk_bf16_f32 v198, v198, v199
	v_cvt_pk_bf16_f32 v199, v200, v201
	v_cvt_pk_bf16_f32 v200, v202, v203
	v_cvt_pk_bf16_f32 v201, v204, v205
	global_store_dwordx4 v[190:191], v[198:201], off
	s_nop 1
	s_waitcnt vmcnt(6)
	v_lshlrev_b32_e32 v198, 16, v210
	v_and_b32_e32 v199, 0xffff0000, v210
	v_lshlrev_b32_e32 v200, 16, v211
	v_and_b32_e32 v201, 0xffff0000, v211
	v_lshlrev_b32_e32 v202, 16, v212
	v_and_b32_e32 v203, 0xffff0000, v212
	v_lshlrev_b32_e32 v204, 16, v213
	v_and_b32_e32 v205, 0xffff0000, v213
	v_pk_fma_f32 v[148:149], v[148:149], v[48:49], v[198:199]
	v_pk_fma_f32 v[150:151], v[150:151], v[50:51], v[200:201]
	v_pk_fma_f32 v[144:145], v[144:145], v[56:57], v[202:203]
	v_pk_fma_f32 v[146:147], v[146:147], v[58:59], v[204:205]
	v_cvt_pk_bf16_f32 v210, v148, v149
	v_cvt_pk_bf16_f32 v211, v150, v151
	v_cvt_pk_bf16_f32 v212, v144, v145
	v_cvt_pk_bf16_f32 v213, v146, v147
	global_store_dwordx4 v[186:187], v[210:213], off offset:256
	v_pk_mul_f32 v[198:199], v[44:45], v[148:149]
	v_pk_mul_f32 v[200:201], v[46:47], v[150:151]
	v_pk_mul_f32 v[202:203], v[40:41], v[144:145]
	v_pk_mul_f32 v[204:205], v[42:43], v[146:147]
	v_pk_fma_f32 v[188:189], v[148:149], v[148:149], v[188:189]
	v_pk_fma_f32 v[188:189], v[150:151], v[150:151], v[188:189]
	v_pk_fma_f32 v[188:189], v[144:145], v[144:145], v[188:189]
	v_pk_fma_f32 v[188:189], v[146:147], v[146:147], v[188:189]
	s_mov_b64 s[80:81], 0x8000
	v_lshl_add_u64 v[222:223], v[222:223], 0, s[80:81]
	global_load_dwordx4 v[210:213], v[222:223], off
	v_cvt_pk_bf16_f32 v198, v198, v199
	v_cvt_pk_bf16_f32 v199, v200, v201
	v_cvt_pk_bf16_f32 v200, v202, v203
	v_cvt_pk_bf16_f32 v201, v204, v205
	global_store_dwordx4 v[190:191], v[198:201], off offset:256
	v_add_f32_e32 v202, v188, v189
	v_mov_b32_e32 v203, v202
	s_nop 1
	v_permlane16_swap_b32_e32 v202, v203
	v_add_f32_e32 v202, v202, v203
	v_mov_b32_e32 v203, v202
	s_nop 1
	v_permlane32_swap_b32_e32 v202, v203
	s_and_saveexec_b64 vcc, s[8:9]
	v_add_f32_e32 v202, v202, v203
	global_atomic_add_f32 v[184:185], v202, off
	s_mov_b64 exec, vcc
	s_mov_b64 s[82:83], 0x8000
	v_lshl_add_u64 v[186:187], v[186:187], 0, s[82:83]
	v_lshl_add_u64 v[190:191], v[190:191], 0, s[82:83]
	s_waitcnt vmcnt(9)
	v_lshlrev_b32_e32 v198, 16, v214
	v_and_b32_e32 v199, 0xffff0000, v214
	v_lshlrev_b32_e32 v200, 16, v215
	v_and_b32_e32 v201, 0xffff0000, v215
	v_lshlrev_b32_e32 v202, 16, v216
	v_and_b32_e32 v203, 0xffff0000, v216
	v_lshlrev_b32_e32 v204, 16, v217
	v_and_b32_e32 v205, 0xffff0000, v217
	v_pk_fma_f32 v[140:141], v[140:141], v[72:73], v[198:199]
	v_pk_fma_f32 v[142:143], v[142:143], v[74:75], v[200:201]
	v_pk_fma_f32 v[136:137], v[136:137], v[84:85], v[202:203]
	v_pk_fma_f32 v[138:139], v[138:139], v[86:87], v[204:205]
	v_cvt_pk_bf16_f32 v214, v140, v141
	v_cvt_pk_bf16_f32 v215, v142, v143
	v_cvt_pk_bf16_f32 v216, v136, v137
	v_cvt_pk_bf16_f32 v217, v138, v139
	global_store_dwordx4 v[186:187], v[214:217], off
	v_pk_mul_f32 v[198:199], v[60:61], v[140:141]
	v_pk_mul_f32 v[200:201], v[62:63], v[142:143]
	v_pk_mul_f32 v[202:203], v[52:53], v[136:137]
	v_pk_mul_f32 v[204:205], v[54:55], v[138:139]
	v_pk_mul_f32 v[188:189], v[140:141], v[140:141]
	v_pk_fma_f32 v[188:189], v[142:143], v[142:143], v[188:189]
	v_pk_fma_f32 v[188:189], v[136:137], v[136:137], v[188:189]
	v_pk_fma_f32 v[188:189], v[138:139], v[138:139], v[188:189]
	global_load_dwordx4 v[214:217], v[222:223], off offset:256
	v_cvt_pk_bf16_f32 v198, v198, v199
	v_cvt_pk_bf16_f32 v199, v200, v201
	v_cvt_pk_bf16_f32 v200, v202, v203
	v_cvt_pk_bf16_f32 v201, v204, v205
	global_store_dwordx4 v[190:191], v[198:201], off
	s_nop 1
	s_waitcnt vmcnt(11)
	v_lshlrev_b32_e32 v198, 16, v218
	v_and_b32_e32 v199, 0xffff0000, v218
	v_lshlrev_b32_e32 v200, 16, v219
	v_and_b32_e32 v201, 0xffff0000, v219
	v_lshlrev_b32_e32 v202, 16, v220
	v_and_b32_e32 v203, 0xffff0000, v220
	v_lshlrev_b32_e32 v204, 16, v221
	v_and_b32_e32 v205, 0xffff0000, v221
	v_pk_fma_f32 v[132:133], v[132:133], v[48:49], v[198:199]
	v_pk_fma_f32 v[134:135], v[134:135], v[50:51], v[200:201]
	v_pk_fma_f32 v[128:129], v[128:129], v[56:57], v[202:203]
	v_pk_fma_f32 v[130:131], v[130:131], v[58:59], v[204:205]
	v_cvt_pk_bf16_f32 v218, v132, v133
	v_cvt_pk_bf16_f32 v219, v134, v135
	v_cvt_pk_bf16_f32 v220, v128, v129
	v_cvt_pk_bf16_f32 v221, v130, v131
	global_store_dwordx4 v[186:187], v[218:221], off offset:256
	v_pk_mul_f32 v[198:199], v[44:45], v[132:133]
	v_pk_mul_f32 v[200:201], v[46:47], v[134:135]
	v_pk_mul_f32 v[202:203], v[40:41], v[128:129]
	v_pk_mul_f32 v[204:205], v[42:43], v[130:131]
	v_pk_fma_f32 v[188:189], v[132:133], v[132:133], v[188:189]
	v_pk_fma_f32 v[188:189], v[134:135], v[134:135], v[188:189]
	v_pk_fma_f32 v[188:189], v[128:129], v[128:129], v[188:189]
	v_pk_fma_f32 v[188:189], v[130:131], v[130:131], v[188:189]
	s_mov_b64 s[80:81], 0x28000
	v_lshl_add_u64 v[222:223], v[222:223], 0, s[80:81]
	global_load_dwordx4 v[218:221], v[222:223], off
	v_cvt_pk_bf16_f32 v198, v198, v199
	v_cvt_pk_bf16_f32 v199, v200, v201
	v_cvt_pk_bf16_f32 v200, v202, v203
	v_cvt_pk_bf16_f32 v201, v204, v205
	global_store_dwordx4 v[190:191], v[198:201], off offset:256
	v_add_f32_e32 v202, v188, v189
	v_mov_b32_e32 v203, v202
	s_nop 1
	v_permlane16_swap_b32_e32 v202, v203
	v_add_f32_e32 v202, v202, v203
	v_mov_b32_e32 v203, v202
	s_nop 1
	v_permlane32_swap_b32_e32 v202, v203
	s_and_saveexec_b64 vcc, s[8:9]
	v_add_f32_e32 v202, v202, v203
	global_atomic_add_f32 v[184:185], v202, off offset:64
	s_mov_b64 exec, vcc
	s_mov_b64 s[82:83], 0x8000
	v_lshl_add_u64 v[186:187], v[186:187], 0, s[82:83]
	v_lshl_add_u64 v[190:191], v[190:191], 0, s[82:83]
	s_waitcnt vmcnt(14)
	v_lshlrev_b32_e32 v198, 16, v236
	v_and_b32_e32 v199, 0xffff0000, v236
	v_lshlrev_b32_e32 v200, 16, v237
	v_and_b32_e32 v201, 0xffff0000, v237
	v_lshlrev_b32_e32 v202, 16, v238
	v_and_b32_e32 v203, 0xffff0000, v238
	v_lshlrev_b32_e32 v204, 16, v239
	v_and_b32_e32 v205, 0xffff0000, v239
	v_pk_fma_f32 v[124:125], v[124:125], v[72:73], v[198:199]
	v_pk_fma_f32 v[126:127], v[126:127], v[74:75], v[200:201]
	v_pk_fma_f32 v[120:121], v[120:121], v[84:85], v[202:203]
	v_pk_fma_f32 v[122:123], v[122:123], v[86:87], v[204:205]
	v_cvt_pk_bf16_f32 v236, v124, v125
	v_cvt_pk_bf16_f32 v237, v126, v127
	v_cvt_pk_bf16_f32 v238, v120, v121
	v_cvt_pk_bf16_f32 v239, v122, v123
	global_store_dwordx4 v[186:187], v[236:239], off
	v_pk_mul_f32 v[198:199], v[60:61], v[124:125]
	v_pk_mul_f32 v[200:201], v[62:63], v[126:127]
	v_pk_mul_f32 v[202:203], v[52:53], v[120:121]
	v_pk_mul_f32 v[204:205], v[54:55], v[122:123]
	v_pk_mul_f32 v[188:189], v[124:125], v[124:125]
	v_pk_fma_f32 v[188:189], v[126:127], v[126:127], v[188:189]
	v_pk_fma_f32 v[188:189], v[120:121], v[120:121], v[188:189]
	v_pk_fma_f32 v[188:189], v[122:123], v[122:123], v[188:189]
	global_load_dwordx4 v[236:239], v[222:223], off offset:256
	v_cvt_pk_bf16_f32 v198, v198, v199
	v_cvt_pk_bf16_f32 v199, v200, v201
	v_cvt_pk_bf16_f32 v200, v202, v203
	v_cvt_pk_bf16_f32 v201, v204, v205
	global_store_dwordx4 v[190:191], v[198:201], off
	s_nop 1
	s_waitcnt vmcnt(15)
	v_lshlrev_b32_e32 v198, 16, v206
	v_and_b32_e32 v199, 0xffff0000, v206
	v_lshlrev_b32_e32 v200, 16, v207
	v_and_b32_e32 v201, 0xffff0000, v207
	v_lshlrev_b32_e32 v202, 16, v208
	v_and_b32_e32 v203, 0xffff0000, v208
	v_lshlrev_b32_e32 v204, 16, v209
	v_and_b32_e32 v205, 0xffff0000, v209
	v_pk_fma_f32 v[116:117], v[116:117], v[48:49], v[198:199]
	v_pk_fma_f32 v[118:119], v[118:119], v[50:51], v[200:201]
	v_pk_fma_f32 v[112:113], v[112:113], v[56:57], v[202:203]
	v_pk_fma_f32 v[114:115], v[114:115], v[58:59], v[204:205]
	v_cvt_pk_bf16_f32 v206, v116, v117
	v_cvt_pk_bf16_f32 v207, v118, v119
	v_cvt_pk_bf16_f32 v208, v112, v113
	v_cvt_pk_bf16_f32 v209, v114, v115
	global_store_dwordx4 v[186:187], v[206:209], off offset:256
	v_pk_mul_f32 v[198:199], v[44:45], v[116:117]
	v_pk_mul_f32 v[200:201], v[46:47], v[118:119]
	v_pk_mul_f32 v[202:203], v[40:41], v[112:113]
	v_pk_mul_f32 v[204:205], v[42:43], v[114:115]
	v_pk_fma_f32 v[188:189], v[116:117], v[116:117], v[188:189]
	v_pk_fma_f32 v[188:189], v[118:119], v[118:119], v[188:189]
	v_pk_fma_f32 v[188:189], v[112:113], v[112:113], v[188:189]
	v_pk_fma_f32 v[188:189], v[114:115], v[114:115], v[188:189]
	s_mov_b64 s[80:81], 0x8000
	v_lshl_add_u64 v[222:223], v[222:223], 0, s[80:81]
	global_load_dwordx4 v[206:209], v[222:223], off
	v_cvt_pk_bf16_f32 v198, v198, v199
	v_cvt_pk_bf16_f32 v199, v200, v201
	v_cvt_pk_bf16_f32 v200, v202, v203
	v_cvt_pk_bf16_f32 v201, v204, v205
	global_store_dwordx4 v[190:191], v[198:201], off offset:256
	v_add_f32_e32 v202, v188, v189
	v_mov_b32_e32 v203, v202
	s_nop 1
	v_permlane16_swap_b32_e32 v202, v203
	v_add_f32_e32 v202, v202, v203
	v_mov_b32_e32 v203, v202
	s_nop 1
	v_permlane32_swap_b32_e32 v202, v203
	s_and_saveexec_b64 vcc, s[8:9]
	v_add_f32_e32 v202, v202, v203
	global_atomic_add_f32 v[184:185], v202, off offset:128
	s_mov_b64 exec, vcc
	s_mov_b64 s[82:83], 0x8000
	v_lshl_add_u64 v[186:187], v[186:187], 0, s[82:83]
	v_lshl_add_u64 v[190:191], v[190:191], 0, s[82:83]
	s_waitcnt vmcnt(16)
	v_lshlrev_b32_e32 v198, 16, v210
	v_and_b32_e32 v199, 0xffff0000, v210
	v_lshlrev_b32_e32 v200, 16, v211
	v_and_b32_e32 v201, 0xffff0000, v211
	v_lshlrev_b32_e32 v202, 16, v212
	v_and_b32_e32 v203, 0xffff0000, v212
	v_lshlrev_b32_e32 v204, 16, v213
	v_and_b32_e32 v205, 0xffff0000, v213
	v_pk_fma_f32 v[108:109], v[108:109], v[72:73], v[198:199]
	v_pk_fma_f32 v[110:111], v[110:111], v[74:75], v[200:201]
	v_pk_fma_f32 v[104:105], v[104:105], v[84:85], v[202:203]
	v_pk_fma_f32 v[106:107], v[106:107], v[86:87], v[204:205]
	v_cvt_pk_bf16_f32 v210, v108, v109
	v_cvt_pk_bf16_f32 v211, v110, v111
	v_cvt_pk_bf16_f32 v212, v104, v105
	v_cvt_pk_bf16_f32 v213, v106, v107
	global_store_dwordx4 v[186:187], v[210:213], off
	v_pk_mul_f32 v[198:199], v[60:61], v[108:109]
	v_pk_mul_f32 v[200:201], v[62:63], v[110:111]
	v_pk_mul_f32 v[202:203], v[52:53], v[104:105]
	v_pk_mul_f32 v[204:205], v[54:55], v[106:107]
	v_pk_mul_f32 v[188:189], v[108:109], v[108:109]
	v_pk_fma_f32 v[188:189], v[110:111], v[110:111], v[188:189]
	v_pk_fma_f32 v[188:189], v[104:105], v[104:105], v[188:189]
	v_pk_fma_f32 v[188:189], v[106:107], v[106:107], v[188:189]
	global_load_dwordx4 v[210:213], v[222:223], off offset:256
	v_cvt_pk_bf16_f32 v198, v198, v199
	v_cvt_pk_bf16_f32 v199, v200, v201
	v_cvt_pk_bf16_f32 v200, v202, v203
	v_cvt_pk_bf16_f32 v201, v204, v205
	global_store_dwordx4 v[190:191], v[198:201], off
	s_nop 1
	s_waitcnt vmcnt(15)
	v_lshlrev_b32_e32 v198, 16, v214
	v_and_b32_e32 v199, 0xffff0000, v214
	v_lshlrev_b32_e32 v200, 16, v215
	v_and_b32_e32 v201, 0xffff0000, v215
	v_lshlrev_b32_e32 v202, 16, v216
	v_and_b32_e32 v203, 0xffff0000, v216
	v_lshlrev_b32_e32 v204, 16, v217
	v_and_b32_e32 v205, 0xffff0000, v217
	v_pk_fma_f32 v[100:101], v[100:101], v[48:49], v[198:199]
	v_pk_fma_f32 v[102:103], v[102:103], v[50:51], v[200:201]
	v_pk_fma_f32 v[96:97], v[96:97], v[56:57], v[202:203]
	v_pk_fma_f32 v[98:99], v[98:99], v[58:59], v[204:205]
	v_cvt_pk_bf16_f32 v214, v100, v101
	v_cvt_pk_bf16_f32 v215, v102, v103
	v_cvt_pk_bf16_f32 v216, v96, v97
	v_cvt_pk_bf16_f32 v217, v98, v99
	global_store_dwordx4 v[186:187], v[214:217], off offset:256
	v_pk_mul_f32 v[198:199], v[44:45], v[100:101]
	v_pk_mul_f32 v[200:201], v[46:47], v[102:103]
	v_pk_mul_f32 v[202:203], v[40:41], v[96:97]
	v_pk_mul_f32 v[204:205], v[42:43], v[98:99]
	v_pk_fma_f32 v[188:189], v[100:101], v[100:101], v[188:189]
	v_pk_fma_f32 v[188:189], v[102:103], v[102:103], v[188:189]
	v_pk_fma_f32 v[188:189], v[96:97], v[96:97], v[188:189]
	v_pk_fma_f32 v[188:189], v[98:99], v[98:99], v[188:189]
	s_mov_b64 s[80:81], 0x8000
	v_lshl_add_u64 v[222:223], v[222:223], 0, s[80:81]
	global_load_dwordx4 v[214:217], v[222:223], off
	v_cvt_pk_bf16_f32 v198, v198, v199
	v_cvt_pk_bf16_f32 v199, v200, v201
	v_cvt_pk_bf16_f32 v200, v202, v203
	v_cvt_pk_bf16_f32 v201, v204, v205
	global_store_dwordx4 v[190:191], v[198:201], off offset:256
	v_add_f32_e32 v202, v188, v189
	v_mov_b32_e32 v203, v202
	s_nop 1
	v_permlane16_swap_b32_e32 v202, v203
	v_add_f32_e32 v202, v202, v203
	v_mov_b32_e32 v203, v202
	s_nop 1
	v_permlane32_swap_b32_e32 v202, v203
	s_and_saveexec_b64 vcc, s[8:9]
	v_add_f32_e32 v202, v202, v203
	global_atomic_add_f32 v[184:185], v202, off offset:192
	s_mov_b64 exec, vcc
	s_mov_b64 s[82:83], 0x28000
	v_lshl_add_u64 v[186:187], v[186:187], 0, s[82:83]
	v_lshl_add_u64 v[190:191], v[190:191], 0, s[82:83]
	s_waitcnt vmcnt(16)
	v_lshlrev_b32_e32 v198, 16, v218
	v_and_b32_e32 v199, 0xffff0000, v218
	v_lshlrev_b32_e32 v200, 16, v219
	v_and_b32_e32 v201, 0xffff0000, v219
	v_lshlrev_b32_e32 v202, 16, v220
	v_and_b32_e32 v203, 0xffff0000, v220
	v_lshlrev_b32_e32 v204, 16, v221
	v_and_b32_e32 v205, 0xffff0000, v221
	v_pk_fma_f32 v[92:93], v[92:93], v[72:73], v[198:199]
	v_pk_fma_f32 v[94:95], v[94:95], v[74:75], v[200:201]
	v_pk_fma_f32 v[88:89], v[88:89], v[84:85], v[202:203]
	v_pk_fma_f32 v[90:91], v[90:91], v[86:87], v[204:205]
	v_cvt_pk_bf16_f32 v218, v92, v93
	v_cvt_pk_bf16_f32 v219, v94, v95
	v_cvt_pk_bf16_f32 v220, v88, v89
	v_cvt_pk_bf16_f32 v221, v90, v91
	global_store_dwordx4 v[186:187], v[218:221], off
	v_pk_mul_f32 v[198:199], v[60:61], v[92:93]
	v_pk_mul_f32 v[200:201], v[62:63], v[94:95]
	v_pk_mul_f32 v[202:203], v[52:53], v[88:89]
	v_pk_mul_f32 v[204:205], v[54:55], v[90:91]
	v_pk_mul_f32 v[188:189], v[92:93], v[92:93]
	v_pk_fma_f32 v[188:189], v[94:95], v[94:95], v[188:189]
	v_pk_fma_f32 v[188:189], v[88:89], v[88:89], v[188:189]
	v_pk_fma_f32 v[188:189], v[90:91], v[90:91], v[188:189]
	global_load_dwordx4 v[218:221], v[222:223], off offset:256
	v_cvt_pk_bf16_f32 v198, v198, v199
	v_cvt_pk_bf16_f32 v199, v200, v201
	v_cvt_pk_bf16_f32 v200, v202, v203
	v_cvt_pk_bf16_f32 v201, v204, v205
	global_store_dwordx4 v[190:191], v[198:201], off
	s_nop 1
	s_waitcnt vmcnt(15)
	v_lshlrev_b32_e32 v198, 16, v236
	v_and_b32_e32 v199, 0xffff0000, v236
	v_lshlrev_b32_e32 v200, 16, v237
	v_and_b32_e32 v201, 0xffff0000, v237
	v_lshlrev_b32_e32 v202, 16, v238
	v_and_b32_e32 v203, 0xffff0000, v238
	v_lshlrev_b32_e32 v204, 16, v239
	v_and_b32_e32 v205, 0xffff0000, v239
	v_pk_fma_f32 v[80:81], v[80:81], v[48:49], v[198:199]
	v_pk_fma_f32 v[82:83], v[82:83], v[50:51], v[200:201]
	v_pk_fma_f32 v[76:77], v[76:77], v[56:57], v[202:203]
	v_pk_fma_f32 v[78:79], v[78:79], v[58:59], v[204:205]
	v_cvt_pk_bf16_f32 v236, v80, v81
	v_cvt_pk_bf16_f32 v237, v82, v83
	v_cvt_pk_bf16_f32 v238, v76, v77
	v_cvt_pk_bf16_f32 v239, v78, v79
	global_store_dwordx4 v[186:187], v[236:239], off offset:256
	v_pk_mul_f32 v[198:199], v[44:45], v[80:81]
	v_pk_mul_f32 v[200:201], v[46:47], v[82:83]
	v_pk_mul_f32 v[202:203], v[40:41], v[76:77]
	v_pk_mul_f32 v[204:205], v[42:43], v[78:79]
	v_pk_fma_f32 v[188:189], v[80:81], v[80:81], v[188:189]
	v_pk_fma_f32 v[188:189], v[82:83], v[82:83], v[188:189]
	v_pk_fma_f32 v[188:189], v[76:77], v[76:77], v[188:189]
	v_pk_fma_f32 v[188:189], v[78:79], v[78:79], v[188:189]
	s_mov_b64 s[80:81], 0x8000
	v_lshl_add_u64 v[222:223], v[222:223], 0, s[80:81]
	global_load_dwordx4 v[236:239], v[222:223], off
	v_cvt_pk_bf16_f32 v198, v198, v199
	v_cvt_pk_bf16_f32 v199, v200, v201
	v_cvt_pk_bf16_f32 v200, v202, v203
	v_cvt_pk_bf16_f32 v201, v204, v205
	global_store_dwordx4 v[190:191], v[198:201], off offset:256
	v_add_f32_e32 v202, v188, v189
	v_mov_b32_e32 v203, v202
	s_nop 1
	v_permlane16_swap_b32_e32 v202, v203
	v_add_f32_e32 v202, v202, v203
	v_mov_b32_e32 v203, v202
	s_nop 1
	v_permlane32_swap_b32_e32 v202, v203
	s_and_saveexec_b64 vcc, s[8:9]
	v_add_f32_e32 v202, v202, v203
	global_atomic_add_f32 v[184:185], v202, off offset:512
	s_mov_b64 exec, vcc
	s_mov_b64 s[82:83], 0x8000
	v_lshl_add_u64 v[186:187], v[186:187], 0, s[82:83]
	v_lshl_add_u64 v[190:191], v[190:191], 0, s[82:83]
	s_waitcnt vmcnt(16)
	v_lshlrev_b32_e32 v198, 16, v206
	v_and_b32_e32 v199, 0xffff0000, v206
	v_lshlrev_b32_e32 v200, 16, v207
	v_and_b32_e32 v201, 0xffff0000, v207
	v_lshlrev_b32_e32 v202, 16, v208
	v_and_b32_e32 v203, 0xffff0000, v208
	v_lshlrev_b32_e32 v204, 16, v209
	v_and_b32_e32 v205, 0xffff0000, v209
	v_pk_fma_f32 v[68:69], v[68:69], v[72:73], v[198:199]
	v_pk_fma_f32 v[70:71], v[70:71], v[74:75], v[200:201]
	v_pk_fma_f32 v[64:65], v[64:65], v[84:85], v[202:203]
	v_pk_fma_f32 v[66:67], v[66:67], v[86:87], v[204:205]
	v_cvt_pk_bf16_f32 v206, v68, v69
	v_cvt_pk_bf16_f32 v207, v70, v71
	v_cvt_pk_bf16_f32 v208, v64, v65
	v_cvt_pk_bf16_f32 v209, v66, v67
	global_store_dwordx4 v[186:187], v[206:209], off
	v_pk_mul_f32 v[198:199], v[60:61], v[68:69]
	v_pk_mul_f32 v[200:201], v[62:63], v[70:71]
	v_pk_mul_f32 v[202:203], v[52:53], v[64:65]
	v_pk_mul_f32 v[204:205], v[54:55], v[66:67]
	v_pk_mul_f32 v[188:189], v[68:69], v[68:69]
	v_pk_fma_f32 v[188:189], v[70:71], v[70:71], v[188:189]
	v_pk_fma_f32 v[188:189], v[64:65], v[64:65], v[188:189]
	v_pk_fma_f32 v[188:189], v[66:67], v[66:67], v[188:189]
	global_load_dwordx4 v[206:209], v[222:223], off offset:256
	v_cvt_pk_bf16_f32 v198, v198, v199
	v_cvt_pk_bf16_f32 v199, v200, v201
	v_cvt_pk_bf16_f32 v200, v202, v203
	v_cvt_pk_bf16_f32 v201, v204, v205
	global_store_dwordx4 v[190:191], v[198:201], off
	s_nop 1
	s_waitcnt vmcnt(15)
	v_lshlrev_b32_e32 v198, 16, v210
	v_and_b32_e32 v199, 0xffff0000, v210
	v_lshlrev_b32_e32 v200, 16, v211
	v_and_b32_e32 v201, 0xffff0000, v211
	v_lshlrev_b32_e32 v202, 16, v212
	v_and_b32_e32 v203, 0xffff0000, v212
	v_lshlrev_b32_e32 v204, 16, v213
	v_and_b32_e32 v205, 0xffff0000, v213
	v_pk_fma_f32 v[36:37], v[36:37], v[48:49], v[198:199]
	v_pk_fma_f32 v[38:39], v[38:39], v[50:51], v[200:201]
	v_pk_fma_f32 v[32:33], v[32:33], v[56:57], v[202:203]
	v_pk_fma_f32 v[34:35], v[34:35], v[58:59], v[204:205]
	v_cvt_pk_bf16_f32 v210, v36, v37
	v_cvt_pk_bf16_f32 v211, v38, v39
	v_cvt_pk_bf16_f32 v212, v32, v33
	v_cvt_pk_bf16_f32 v213, v34, v35
	global_store_dwordx4 v[186:187], v[210:213], off offset:256
	v_pk_mul_f32 v[198:199], v[44:45], v[36:37]
	v_pk_mul_f32 v[200:201], v[46:47], v[38:39]
	v_pk_mul_f32 v[202:203], v[40:41], v[32:33]
	v_pk_mul_f32 v[204:205], v[42:43], v[34:35]
	v_pk_fma_f32 v[188:189], v[36:37], v[36:37], v[188:189]
	v_pk_fma_f32 v[188:189], v[38:39], v[38:39], v[188:189]
	v_pk_fma_f32 v[188:189], v[32:33], v[32:33], v[188:189]
	v_pk_fma_f32 v[188:189], v[34:35], v[34:35], v[188:189]
	v_cvt_pk_bf16_f32 v198, v198, v199
	v_cvt_pk_bf16_f32 v199, v200, v201
	v_cvt_pk_bf16_f32 v200, v202, v203
	v_cvt_pk_bf16_f32 v201, v204, v205
	global_store_dwordx4 v[190:191], v[198:201], off offset:256
	v_add_f32_e32 v202, v188, v189
	v_mov_b32_e32 v203, v202
	s_nop 1
	v_permlane16_swap_b32_e32 v202, v203
	v_add_f32_e32 v202, v202, v203
	v_mov_b32_e32 v203, v202
	s_nop 1
	v_permlane32_swap_b32_e32 v202, v203
	s_and_saveexec_b64 vcc, s[8:9]
	v_add_f32_e32 v202, v202, v203
	global_atomic_add_f32 v[184:185], v202, off offset:576
	s_mov_b64 exec, vcc
	s_mov_b64 s[82:83], 0x8000
	v_lshl_add_u64 v[186:187], v[186:187], 0, s[82:83]
	v_lshl_add_u64 v[190:191], v[190:191], 0, s[82:83]
	s_waitcnt vmcnt(15)
	v_lshlrev_b32_e32 v198, 16, v214
	v_and_b32_e32 v199, 0xffff0000, v214
	v_lshlrev_b32_e32 v200, 16, v215
	v_and_b32_e32 v201, 0xffff0000, v215
	v_lshlrev_b32_e32 v202, 16, v216
	v_and_b32_e32 v203, 0xffff0000, v216
	v_lshlrev_b32_e32 v204, 16, v217
	v_and_b32_e32 v205, 0xffff0000, v217
	v_pk_fma_f32 v[28:29], v[28:29], v[72:73], v[198:199]
	v_pk_fma_f32 v[30:31], v[30:31], v[74:75], v[200:201]
	v_pk_fma_f32 v[24:25], v[24:25], v[84:85], v[202:203]
	v_pk_fma_f32 v[26:27], v[26:27], v[86:87], v[204:205]
	v_cvt_pk_bf16_f32 v214, v28, v29
	v_cvt_pk_bf16_f32 v215, v30, v31
	v_cvt_pk_bf16_f32 v216, v24, v25
	v_cvt_pk_bf16_f32 v217, v26, v27
	global_store_dwordx4 v[186:187], v[214:217], off
	v_pk_mul_f32 v[198:199], v[60:61], v[28:29]
	v_pk_mul_f32 v[200:201], v[62:63], v[30:31]
	v_pk_mul_f32 v[202:203], v[52:53], v[24:25]
	v_pk_mul_f32 v[204:205], v[54:55], v[26:27]
	v_pk_mul_f32 v[188:189], v[28:29], v[28:29]
	v_pk_fma_f32 v[188:189], v[30:31], v[30:31], v[188:189]
	v_pk_fma_f32 v[188:189], v[24:25], v[24:25], v[188:189]
	v_pk_fma_f32 v[188:189], v[26:27], v[26:27], v[188:189]
	v_cvt_pk_bf16_f32 v198, v198, v199
	v_cvt_pk_bf16_f32 v199, v200, v201
	v_cvt_pk_bf16_f32 v200, v202, v203
	v_cvt_pk_bf16_f32 v201, v204, v205
	global_store_dwordx4 v[190:191], v[198:201], off
	s_nop 1
	s_waitcnt vmcnt(13)
	v_lshlrev_b32_e32 v198, 16, v218
	v_and_b32_e32 v199, 0xffff0000, v218
	v_lshlrev_b32_e32 v200, 16, v219
	v_and_b32_e32 v201, 0xffff0000, v219
	v_lshlrev_b32_e32 v202, 16, v220
	v_and_b32_e32 v203, 0xffff0000, v220
	v_lshlrev_b32_e32 v204, 16, v221
	v_and_b32_e32 v205, 0xffff0000, v221
	v_pk_fma_f32 v[20:21], v[20:21], v[48:49], v[198:199]
	v_pk_fma_f32 v[22:23], v[22:23], v[50:51], v[200:201]
	v_pk_fma_f32 v[16:17], v[16:17], v[56:57], v[202:203]
	v_pk_fma_f32 v[18:19], v[18:19], v[58:59], v[204:205]
	v_cvt_pk_bf16_f32 v218, v20, v21
	v_cvt_pk_bf16_f32 v219, v22, v23
	v_cvt_pk_bf16_f32 v220, v16, v17
	v_cvt_pk_bf16_f32 v221, v18, v19
	global_store_dwordx4 v[186:187], v[218:221], off offset:256
	v_pk_mul_f32 v[198:199], v[44:45], v[20:21]
	v_pk_mul_f32 v[200:201], v[46:47], v[22:23]
	v_pk_mul_f32 v[202:203], v[40:41], v[16:17]
	v_pk_mul_f32 v[204:205], v[42:43], v[18:19]
	v_pk_fma_f32 v[188:189], v[20:21], v[20:21], v[188:189]
	v_pk_fma_f32 v[188:189], v[22:23], v[22:23], v[188:189]
	v_pk_fma_f32 v[188:189], v[16:17], v[16:17], v[188:189]
	v_pk_fma_f32 v[188:189], v[18:19], v[18:19], v[188:189]
	v_cvt_pk_bf16_f32 v198, v198, v199
	v_cvt_pk_bf16_f32 v199, v200, v201
	v_cvt_pk_bf16_f32 v200, v202, v203
	v_cvt_pk_bf16_f32 v201, v204, v205
	global_store_dwordx4 v[190:191], v[198:201], off offset:256
	v_add_f32_e32 v202, v188, v189
	v_mov_b32_e32 v203, v202
	s_nop 1
	v_permlane16_swap_b32_e32 v202, v203
	v_add_f32_e32 v202, v202, v203
	v_mov_b32_e32 v203, v202
	s_nop 1
	v_permlane32_swap_b32_e32 v202, v203
	s_and_saveexec_b64 vcc, s[8:9]
	v_add_f32_e32 v202, v202, v203
	global_atomic_add_f32 v[184:185], v202, off offset:640
	s_mov_b64 exec, vcc
	s_mov_b64 s[82:83], 0x8000
	v_lshl_add_u64 v[186:187], v[186:187], 0, s[82:83]
	v_lshl_add_u64 v[190:191], v[190:191], 0, s[82:83]
	s_waitcnt vmcnt(13)
	v_lshlrev_b32_e32 v198, 16, v236
	v_and_b32_e32 v199, 0xffff0000, v236
	v_lshlrev_b32_e32 v200, 16, v237
	v_and_b32_e32 v201, 0xffff0000, v237
	v_lshlrev_b32_e32 v202, 16, v238
	v_and_b32_e32 v203, 0xffff0000, v238
	v_lshlrev_b32_e32 v204, 16, v239
	v_and_b32_e32 v205, 0xffff0000, v239
	v_pk_fma_f32 v[12:13], v[12:13], v[72:73], v[198:199]
	v_pk_fma_f32 v[14:15], v[14:15], v[74:75], v[200:201]
	v_pk_fma_f32 v[8:9], v[8:9], v[84:85], v[202:203]
	v_pk_fma_f32 v[10:11], v[10:11], v[86:87], v[204:205]
	v_cvt_pk_bf16_f32 v236, v12, v13
	v_cvt_pk_bf16_f32 v237, v14, v15
	v_cvt_pk_bf16_f32 v238, v8, v9
	v_cvt_pk_bf16_f32 v239, v10, v11
	global_store_dwordx4 v[186:187], v[236:239], off
	v_pk_mul_f32 v[198:199], v[60:61], v[12:13]
	v_pk_mul_f32 v[200:201], v[62:63], v[14:15]
	v_pk_mul_f32 v[202:203], v[52:53], v[8:9]
	v_pk_mul_f32 v[204:205], v[54:55], v[10:11]
	v_pk_mul_f32 v[188:189], v[12:13], v[12:13]
	v_pk_fma_f32 v[188:189], v[14:15], v[14:15], v[188:189]
	v_pk_fma_f32 v[188:189], v[8:9], v[8:9], v[188:189]
	v_pk_fma_f32 v[188:189], v[10:11], v[10:11], v[188:189]
	v_cvt_pk_bf16_f32 v198, v198, v199
	v_cvt_pk_bf16_f32 v199, v200, v201
	v_cvt_pk_bf16_f32 v200, v202, v203
	v_cvt_pk_bf16_f32 v201, v204, v205
	global_store_dwordx4 v[190:191], v[198:201], off
	s_nop 1
	s_waitcnt vmcnt(11)
	v_lshlrev_b32_e32 v198, 16, v206
	v_and_b32_e32 v199, 0xffff0000, v206
	v_lshlrev_b32_e32 v200, 16, v207
	v_and_b32_e32 v201, 0xffff0000, v207
	v_lshlrev_b32_e32 v202, 16, v208
	v_and_b32_e32 v203, 0xffff0000, v208
	v_lshlrev_b32_e32 v204, 16, v209
	v_and_b32_e32 v205, 0xffff0000, v209
	v_pk_fma_f32 v[4:5], v[4:5], v[48:49], v[198:199]
	v_pk_fma_f32 v[6:7], v[6:7], v[50:51], v[200:201]
	v_pk_fma_f32 v[0:1], v[0:1], v[56:57], v[202:203]
	v_pk_fma_f32 v[2:3], v[2:3], v[58:59], v[204:205]
	v_cvt_pk_bf16_f32 v206, v4, v5
	v_cvt_pk_bf16_f32 v207, v6, v7
	v_cvt_pk_bf16_f32 v208, v0, v1
	v_cvt_pk_bf16_f32 v209, v2, v3
	global_store_dwordx4 v[186:187], v[206:209], off offset:256
	v_pk_mul_f32 v[198:199], v[44:45], v[4:5]
	v_pk_mul_f32 v[200:201], v[46:47], v[6:7]
	v_pk_mul_f32 v[202:203], v[40:41], v[0:1]
	v_pk_mul_f32 v[204:205], v[42:43], v[2:3]
	v_pk_fma_f32 v[188:189], v[4:5], v[4:5], v[188:189]
	v_pk_fma_f32 v[188:189], v[6:7], v[6:7], v[188:189]
	v_pk_fma_f32 v[188:189], v[0:1], v[0:1], v[188:189]
	v_pk_fma_f32 v[188:189], v[2:3], v[2:3], v[188:189]
	v_cvt_pk_bf16_f32 v198, v198, v199
	v_cvt_pk_bf16_f32 v199, v200, v201
	v_cvt_pk_bf16_f32 v200, v202, v203
	v_cvt_pk_bf16_f32 v201, v204, v205
	global_store_dwordx4 v[190:191], v[198:201], off offset:256
	v_add_f32_e32 v202, v188, v189
	v_mov_b32_e32 v203, v202
	s_nop 1
	v_permlane16_swap_b32_e32 v202, v203
	v_add_f32_e32 v202, v202, v203
	v_mov_b32_e32 v203, v202
	s_nop 1
	v_permlane32_swap_b32_e32 v202, v203
	s_and_saveexec_b64 vcc, s[8:9]
	v_add_f32_e32 v202, v202, v203
	global_atomic_add_f32 v[184:185], v202, off offset:704
	s_mov_b64 exec, vcc
	s_branch .LBB0_1041
